# EpiMlpIn v2 with write-through (sc1) output stores
# speedup vs baseline: 1.0055x; 1.0055x over previous
; __device__ __forceinline__ u32x4 pack8(const f32x4 v0, const f32x4 v1) { u32x4 w; w.x = cvt_pk_bf16(v0[0], v0[1]); w.y = cvt_pk_bf16(v0[2], v0[3]); w.z = cvt_pk_bf16(v1[0], v1[1]); w.w = cvt_pk_bf16(v1[2], v1[3]); return w; }
; __device__ __forceinline__ void row_rs8(float (&rs)[8], const float* ssq, int row0, int fq) {
;     f32x4 p[8];
; #pragma unroll
;     for (int i = 0; i < 8; ++i) p[i] = *(const f32x4*)(ssq + (size_t)(row0 + (i >> 2) * HALF + (i & 3) * 16) * 16 + 4 * fq);
; #pragma unroll
;     for (int i = 0; i < 8; ++i) { float s = (p[i][0] + p[i][1]) + (p[i][2] + p[i][3]); s += __shfl_xor(s, 16); s += __shfl_xor(s, 32); rs[i] = __builtin_amdgcn_rsqf(s * (1.0f / DMODEL) + RMS_EPS); }
;     __device__ __forceinline__ void operator()(const f32x4 (&acc)[2][2][4][2], const Unit& u, int wr, int wc, int fr, int fq) const {
;         const int row0 = u.pm * BM + wr * 64 + fr, col0 = u.pn * BM + wc * 32 + 8 * fq;
;         float rs[8]; row_rs8(rs, ssq, row0, fq);
; #pragma unroll
;         for (int ai = 0; ai < 2; ++ai)
; #pragma unroll
;             for (int m = 0; m < 4; ++m) { const int row = row0 + ai * HALF + m * 16; const float r = rs[ai * 4 + m];
;                 bf16_t* rowp = O + (size_t)row * ldc + col0;
; #pragma unroll
;                 for (int bj = 0; bj < 2; ++bj) { f32x4 v0 = acc[ai][bj][m][0] * r, v1 = acc[ai][bj][m][1] * r;
; #pragma unroll
;                     for (int e = 0; e < 4; ++e) { const float a = fmaxf(v0[e], 0.f), b = fmaxf(v1[e], 0.f); v0[e] = a * a; v1[e] = b * b; }
;                     *(u32x4*)(rowp + bj * HALF) = pack8(v0, v1); } }
.LBB0_614:
	v_readfirstlane_b32 s11, v192
	v_and_b32_e32 v176, 15, v192
	s_lshl_b32 s13, s22, 8
	s_lshr_b32 s22, s11, 8
	s_lshl_b32 s22, s22, 6
	s_add_i32 s22, s22, s13
	v_add_u32_e32 v176, s22, v176
	v_bfe_u32 v177, v192, 4, 2
	s_lshr_b32 s11, s11, 1
	s_and_b32 s11, s11, 0x60
	s_lshl_b32 s13, s20, 8
	s_or_b32 s11, s11, s13
	v_lshl_or_b32 v178, v177, 3, s11
	v_lshlrev_b32_e32 v172, 13, v176
	v_lshl_add_u32 v172, v178, 1, v172
	v_lshlrev_b32_e32 v173, 6, v176
	v_lshl_add_u32 v173, v177, 4, v173
	global_load_dwordx4 v[128:131], v173, s[6:7]
	v_add_u32_e32 v178, 0x400, v173
	global_load_dwordx4 v[132:135], v178, s[6:7]
	v_add_u32_e32 v178, 0x800, v173
	global_load_dwordx4 v[136:139], v178, s[6:7]
	v_add_u32_e32 v178, 0xc00, v173
	global_load_dwordx4 v[140:143], v178, s[6:7]
	v_add_u32_e32 v178, 0x2000, v173
	global_load_dwordx4 v[144:147], v178, s[6:7]
	v_add_u32_e32 v178, 0x2400, v173
	global_load_dwordx4 v[148:151], v178, s[6:7]
	v_add_u32_e32 v178, 0x2800, v173
	global_load_dwordx4 v[164:167], v178, s[6:7]
	v_add_u32_e32 v178, 0x2c00, v173
	global_load_dwordx4 v[168:171], v178, s[6:7]
	v_xor_b32_e32 v174, 16, v241
	v_xor_b32_e32 v175, 32, v241
	v_lshlrev_b32_e32 v174, 2, v174
	v_lshlrev_b32_e32 v175, 2, v175
	s_waitcnt vmcnt(7)
	v_add_f32_e32 v176, v128, v129
	v_add_f32_e32 v177, v130, v131
	v_add_f32_e32 v176, v176, v177
	ds_bpermute_b32 v177, v174, v176
	s_waitcnt lgkmcnt(0)
	v_add_f32_e32 v176, v176, v177
	ds_bpermute_b32 v177, v175, v176
	v_mov_b32_e32 v178, v172
	s_waitcnt lgkmcnt(0)
	v_add_f32_e32 v176, v176, v177
	v_fmamk_f32 v176, v176, 0x3a800000, v193
	v_rsq_f32_e32 v180, v176
	s_nop 0
	v_pk_mul_f32 v[124:125], v[124:125], v[180:181] op_sel_hi:[1,0]
	v_pk_mul_f32 v[126:127], v[126:127], v[180:181] op_sel_hi:[1,0]
	v_pk_mul_f32 v[120:121], v[120:121], v[180:181] op_sel_hi:[1,0]
	v_pk_mul_f32 v[122:123], v[122:123], v[180:181] op_sel_hi:[1,0]
	v_max_f32_e32 v124, 0, v124
	v_max_f32_e32 v125, 0, v125
	v_max_f32_e32 v126, 0, v126
	v_max_f32_e32 v127, 0, v127
	v_max_f32_e32 v120, 0, v120
	v_max_f32_e32 v121, 0, v121
	v_max_f32_e32 v122, 0, v122
	v_max_f32_e32 v123, 0, v123
	v_pk_mul_f32 v[124:125], v[124:125], v[124:125]
	v_pk_mul_f32 v[126:127], v[126:127], v[126:127]
	v_pk_mul_f32 v[120:121], v[120:121], v[120:121]
	v_pk_mul_f32 v[122:123], v[122:123], v[122:123]
	v_cvt_pk_bf16_f32 v124, v124, v125
	v_cvt_pk_bf16_f32 v125, v126, v127
	v_cvt_pk_bf16_f32 v126, v120, v121
	v_cvt_pk_bf16_f32 v127, v122, v123
	global_store_dwordx4 v178, v[124:127], s[0:1] sc1
	v_pk_mul_f32 v[116:117], v[116:117], v[180:181] op_sel_hi:[1,0]
	v_pk_mul_f32 v[118:119], v[118:119], v[180:181] op_sel_hi:[1,0]
	v_pk_mul_f32 v[112:113], v[112:113], v[180:181] op_sel_hi:[1,0]
	v_pk_mul_f32 v[114:115], v[114:115], v[180:181] op_sel_hi:[1,0]
	v_max_f32_e32 v116, 0, v116
	v_max_f32_e32 v117, 0, v117
	v_max_f32_e32 v118, 0, v118
	v_max_f32_e32 v119, 0, v119
	v_max_f32_e32 v112, 0, v112
	v_max_f32_e32 v113, 0, v113
	v_max_f32_e32 v114, 0, v114
	v_max_f32_e32 v115, 0, v115
	v_pk_mul_f32 v[116:117], v[116:117], v[116:117]
	v_pk_mul_f32 v[118:119], v[118:119], v[118:119]
	v_pk_mul_f32 v[112:113], v[112:113], v[112:113]
	v_pk_mul_f32 v[114:115], v[114:115], v[114:115]
	v_cvt_pk_bf16_f32 v116, v116, v117
	v_cvt_pk_bf16_f32 v117, v118, v119
	v_cvt_pk_bf16_f32 v118, v112, v113
	v_cvt_pk_bf16_f32 v119, v114, v115
	global_store_dwordx4 v178, v[116:119], s[0:1] offset:256 sc1
	s_waitcnt vmcnt(8)
	v_add_f32_e32 v176, v132, v133
	v_add_f32_e32 v177, v134, v135
	v_add_f32_e32 v176, v176, v177
	ds_bpermute_b32 v177, v174, v176
	s_waitcnt lgkmcnt(0)
	v_add_f32_e32 v176, v176, v177
	ds_bpermute_b32 v177, v175, v176
	v_add_u32_e32 v178, 0x20000, v172
	s_waitcnt lgkmcnt(0)
	v_add_f32_e32 v176, v176, v177
	v_fmamk_f32 v176, v176, 0x3a800000, v193
	v_rsq_f32_e32 v180, v176
	s_nop 0
	v_pk_mul_f32 v[108:109], v[108:109], v[180:181] op_sel_hi:[1,0]
	v_pk_mul_f32 v[110:111], v[110:111], v[180:181] op_sel_hi:[1,0]
	v_pk_mul_f32 v[104:105], v[104:105], v[180:181] op_sel_hi:[1,0]
	v_pk_mul_f32 v[106:107], v[106:107], v[180:181] op_sel_hi:[1,0]
	v_max_f32_e32 v108, 0, v108
	v_max_f32_e32 v109, 0, v109
	v_max_f32_e32 v110, 0, v110
	v_max_f32_e32 v111, 0, v111
	v_max_f32_e32 v104, 0, v104
	v_max_f32_e32 v105, 0, v105
	v_max_f32_e32 v106, 0, v106
	v_max_f32_e32 v107, 0, v107
	v_pk_mul_f32 v[108:109], v[108:109], v[108:109]
	v_pk_mul_f32 v[110:111], v[110:111], v[110:111]
	v_pk_mul_f32 v[104:105], v[104:105], v[104:105]
	v_pk_mul_f32 v[106:107], v[106:107], v[106:107]
	v_cvt_pk_bf16_f32 v108, v108, v109
	v_cvt_pk_bf16_f32 v109, v110, v111
	v_cvt_pk_bf16_f32 v110, v104, v105
	v_cvt_pk_bf16_f32 v111, v106, v107
	global_store_dwordx4 v178, v[108:111], s[0:1] sc1
	v_pk_mul_f32 v[100:101], v[100:101], v[180:181] op_sel_hi:[1,0]
	v_pk_mul_f32 v[102:103], v[102:103], v[180:181] op_sel_hi:[1,0]
	v_pk_mul_f32 v[96:97], v[96:97], v[180:181] op_sel_hi:[1,0]
	v_pk_mul_f32 v[98:99], v[98:99], v[180:181] op_sel_hi:[1,0]
	v_max_f32_e32 v100, 0, v100
	v_max_f32_e32 v101, 0, v101
	v_max_f32_e32 v102, 0, v102
	v_max_f32_e32 v103, 0, v103
	v_max_f32_e32 v96, 0, v96
	v_max_f32_e32 v97, 0, v97
	v_max_f32_e32 v98, 0, v98
	v_max_f32_e32 v99, 0, v99
	v_pk_mul_f32 v[100:101], v[100:101], v[100:101]
	v_pk_mul_f32 v[102:103], v[102:103], v[102:103]
	v_pk_mul_f32 v[96:97], v[96:97], v[96:97]
	v_pk_mul_f32 v[98:99], v[98:99], v[98:99]
	v_cvt_pk_bf16_f32 v100, v100, v101
	v_cvt_pk_bf16_f32 v101, v102, v103
	v_cvt_pk_bf16_f32 v102, v96, v97
	v_cvt_pk_bf16_f32 v103, v98, v99
	global_store_dwordx4 v178, v[100:103], s[0:1] offset:256 sc1
	s_waitcnt vmcnt(9)
; __device__ __forceinline__ u32x4 pack8(const f32x4 v0, const f32x4 v1) { u32x4 w; w.x = cvt_pk_bf16(v0[0], v0[1]); w.y = cvt_pk_bf16(v0[2], v0[3]); w.z = cvt_pk_bf16(v1[0], v1[1]); w.w = cvt_pk_bf16(v1[2], v1[3]); return w; }
; __device__ __forceinline__ void row_rs8(float (&rs)[8], const float* ssq, int row0, int fq) {
;     ...
;     for (int i = 0; i < 8; ++i) p[i] = *(const f32x4*)(ssq + (size_t)(row0 + (i >> 2) * HALF + (i & 3) * 16) * 16 + 4 * fq);
; #pragma unroll
;     for (int i = 0; i < 8; ++i) { float s = (p[i][0] + p[i][1]) + (p[i][2] + p[i][3]); s += __shfl_xor(s, 16); s += __shfl_xor(s, 32); rs[i] = __builtin_amdgcn_rsqf(s * (1.0f / DMODEL) + RMS_EPS); }
;     __device__ __forceinline__ void operator()(const f32x4 (&acc)[2][2][4][2], const Unit& u, int wr, int wc, int fr, int fq) const {
;     ...
;             for (int m = 0; m < 4; ++m) { const int row = row0 + ai * HALF + m * 16; const float r = rs[ai * 4 + m];
;                 bf16_t* rowp = O + (size_t)row * ldc + col0;
; #pragma unroll
;                 for (int bj = 0; bj < 2; ++bj) { f32x4 v0 = acc[ai][bj][m][0] * r, v1 = acc[ai][bj][m][1] * r;
; #pragma unroll
;                     for (int e = 0; e < 4; ++e) { const float a = fmaxf(v0[e], 0.f), b = fmaxf(v1[e], 0.f); v0[e] = a * a; v1[e] = b * b; }
;                     *(u32x4*)(rowp + bj * HALF) = pack8(v0, v1); } }
	v_add_f32_e32 v176, v136, v137
	v_add_f32_e32 v177, v138, v139
	v_add_f32_e32 v176, v176, v177
	ds_bpermute_b32 v177, v174, v176
	s_waitcnt lgkmcnt(0)
	v_add_f32_e32 v176, v176, v177
	ds_bpermute_b32 v177, v175, v176
	v_add_u32_e32 v178, 0x40000, v172
	s_waitcnt lgkmcnt(0)
	v_add_f32_e32 v176, v176, v177
	v_fmamk_f32 v176, v176, 0x3a800000, v193
	v_rsq_f32_e32 v180, v176
	s_nop 0
	v_pk_mul_f32 v[92:93], v[92:93], v[180:181] op_sel_hi:[1,0]
	v_pk_mul_f32 v[94:95], v[94:95], v[180:181] op_sel_hi:[1,0]
	v_pk_mul_f32 v[88:89], v[88:89], v[180:181] op_sel_hi:[1,0]
	v_pk_mul_f32 v[90:91], v[90:91], v[180:181] op_sel_hi:[1,0]
	v_max_f32_e32 v92, 0, v92
	v_max_f32_e32 v93, 0, v93
	v_max_f32_e32 v94, 0, v94
	v_max_f32_e32 v95, 0, v95
	v_max_f32_e32 v88, 0, v88
	v_max_f32_e32 v89, 0, v89
	v_max_f32_e32 v90, 0, v90
	v_max_f32_e32 v91, 0, v91
	v_pk_mul_f32 v[92:93], v[92:93], v[92:93]
	v_pk_mul_f32 v[94:95], v[94:95], v[94:95]
	v_pk_mul_f32 v[88:89], v[88:89], v[88:89]
	v_pk_mul_f32 v[90:91], v[90:91], v[90:91]
	v_cvt_pk_bf16_f32 v92, v92, v93
	v_cvt_pk_bf16_f32 v93, v94, v95
	v_cvt_pk_bf16_f32 v94, v88, v89
	v_cvt_pk_bf16_f32 v95, v90, v91
	global_store_dwordx4 v178, v[92:95], s[0:1] sc1
	v_pk_mul_f32 v[84:85], v[84:85], v[180:181] op_sel_hi:[1,0]
	v_pk_mul_f32 v[86:87], v[86:87], v[180:181] op_sel_hi:[1,0]
	v_pk_mul_f32 v[80:81], v[80:81], v[180:181] op_sel_hi:[1,0]
	v_pk_mul_f32 v[82:83], v[82:83], v[180:181] op_sel_hi:[1,0]
	v_max_f32_e32 v84, 0, v84
	v_max_f32_e32 v85, 0, v85
	v_max_f32_e32 v86, 0, v86
	v_max_f32_e32 v87, 0, v87
	v_max_f32_e32 v80, 0, v80
	v_max_f32_e32 v81, 0, v81
	v_max_f32_e32 v82, 0, v82
	v_max_f32_e32 v83, 0, v83
	v_pk_mul_f32 v[84:85], v[84:85], v[84:85]
	v_pk_mul_f32 v[86:87], v[86:87], v[86:87]
	v_pk_mul_f32 v[80:81], v[80:81], v[80:81]
	v_pk_mul_f32 v[82:83], v[82:83], v[82:83]
	v_cvt_pk_bf16_f32 v84, v84, v85
	v_cvt_pk_bf16_f32 v85, v86, v87
	v_cvt_pk_bf16_f32 v86, v80, v81
	v_cvt_pk_bf16_f32 v87, v82, v83
	global_store_dwordx4 v178, v[84:87], s[0:1] offset:256 sc1
	s_waitcnt vmcnt(10)
	v_add_f32_e32 v176, v140, v141
	v_add_f32_e32 v177, v142, v143
	v_add_f32_e32 v176, v176, v177
	ds_bpermute_b32 v177, v174, v176
	s_waitcnt lgkmcnt(0)
	v_add_f32_e32 v176, v176, v177
	ds_bpermute_b32 v177, v175, v176
	v_add_u32_e32 v178, 0x60000, v172
	s_waitcnt lgkmcnt(0)
	v_add_f32_e32 v176, v176, v177
	v_fmamk_f32 v176, v176, 0x3a800000, v193
	v_rsq_f32_e32 v180, v176
	s_nop 0
	v_pk_mul_f32 v[76:77], v[76:77], v[180:181] op_sel_hi:[1,0]
	v_pk_mul_f32 v[78:79], v[78:79], v[180:181] op_sel_hi:[1,0]
	v_pk_mul_f32 v[72:73], v[72:73], v[180:181] op_sel_hi:[1,0]
	v_pk_mul_f32 v[74:75], v[74:75], v[180:181] op_sel_hi:[1,0]
	v_max_f32_e32 v76, 0, v76
	v_max_f32_e32 v77, 0, v77
	v_max_f32_e32 v78, 0, v78
	v_max_f32_e32 v79, 0, v79
	v_max_f32_e32 v72, 0, v72
	v_max_f32_e32 v73, 0, v73
	v_max_f32_e32 v74, 0, v74
	v_max_f32_e32 v75, 0, v75
	v_pk_mul_f32 v[76:77], v[76:77], v[76:77]
	v_pk_mul_f32 v[78:79], v[78:79], v[78:79]
	v_pk_mul_f32 v[72:73], v[72:73], v[72:73]
	v_pk_mul_f32 v[74:75], v[74:75], v[74:75]
	v_cvt_pk_bf16_f32 v76, v76, v77
	v_cvt_pk_bf16_f32 v77, v78, v79
	v_cvt_pk_bf16_f32 v78, v72, v73
	v_cvt_pk_bf16_f32 v79, v74, v75
	global_store_dwordx4 v178, v[76:79], s[0:1] sc1
	v_pk_mul_f32 v[68:69], v[68:69], v[180:181] op_sel_hi:[1,0]
	v_pk_mul_f32 v[70:71], v[70:71], v[180:181] op_sel_hi:[1,0]
	v_pk_mul_f32 v[64:65], v[64:65], v[180:181] op_sel_hi:[1,0]
	v_pk_mul_f32 v[66:67], v[66:67], v[180:181] op_sel_hi:[1,0]
	v_max_f32_e32 v68, 0, v68
	v_max_f32_e32 v69, 0, v69
	v_max_f32_e32 v70, 0, v70
	v_max_f32_e32 v71, 0, v71
	v_max_f32_e32 v64, 0, v64
	v_max_f32_e32 v65, 0, v65
	v_max_f32_e32 v66, 0, v66
	v_max_f32_e32 v67, 0, v67
	v_pk_mul_f32 v[68:69], v[68:69], v[68:69]
	v_pk_mul_f32 v[70:71], v[70:71], v[70:71]
	v_pk_mul_f32 v[64:65], v[64:65], v[64:65]
	v_pk_mul_f32 v[66:67], v[66:67], v[66:67]
	v_cvt_pk_bf16_f32 v68, v68, v69
	v_cvt_pk_bf16_f32 v69, v70, v71
	v_cvt_pk_bf16_f32 v70, v64, v65
	v_cvt_pk_bf16_f32 v71, v66, v67
	global_store_dwordx4 v178, v[68:71], s[0:1] offset:256 sc1
	s_waitcnt vmcnt(11)
	v_add_f32_e32 v176, v144, v145
	v_add_f32_e32 v177, v146, v147
	v_add_f32_e32 v176, v176, v177
	ds_bpermute_b32 v177, v174, v176
	s_waitcnt lgkmcnt(0)
	v_add_f32_e32 v176, v176, v177
	ds_bpermute_b32 v177, v175, v176
	v_add_u32_e32 v178, 0x100000, v172
	s_waitcnt lgkmcnt(0)
	v_add_f32_e32 v176, v176, v177
	v_fmamk_f32 v176, v176, 0x3a800000, v193
	v_rsq_f32_e32 v180, v176
	s_nop 0
	v_pk_mul_f32 v[60:61], v[60:61], v[180:181] op_sel_hi:[1,0]
	v_pk_mul_f32 v[62:63], v[62:63], v[180:181] op_sel_hi:[1,0]
	v_pk_mul_f32 v[56:57], v[56:57], v[180:181] op_sel_hi:[1,0]
	v_pk_mul_f32 v[58:59], v[58:59], v[180:181] op_sel_hi:[1,0]
	v_max_f32_e32 v60, 0, v60
	v_max_f32_e32 v61, 0, v61
	v_max_f32_e32 v62, 0, v62
	v_max_f32_e32 v63, 0, v63
	v_max_f32_e32 v56, 0, v56
	v_max_f32_e32 v57, 0, v57
	v_max_f32_e32 v58, 0, v58
	v_max_f32_e32 v59, 0, v59
	v_pk_mul_f32 v[60:61], v[60:61], v[60:61]
	v_pk_mul_f32 v[62:63], v[62:63], v[62:63]
	v_pk_mul_f32 v[56:57], v[56:57], v[56:57]
	v_pk_mul_f32 v[58:59], v[58:59], v[58:59]
	v_cvt_pk_bf16_f32 v60, v60, v61
	v_cvt_pk_bf16_f32 v61, v62, v63
	v_cvt_pk_bf16_f32 v62, v56, v57
	v_cvt_pk_bf16_f32 v63, v58, v59
	global_store_dwordx4 v178, v[60:63], s[0:1] sc1
	v_pk_mul_f32 v[52:53], v[52:53], v[180:181] op_sel_hi:[1,0]
	v_pk_mul_f32 v[54:55], v[54:55], v[180:181] op_sel_hi:[1,0]
	v_pk_mul_f32 v[48:49], v[48:49], v[180:181] op_sel_hi:[1,0]
	v_pk_mul_f32 v[50:51], v[50:51], v[180:181] op_sel_hi:[1,0]
	v_max_f32_e32 v52, 0, v52
	v_max_f32_e32 v53, 0, v53
	v_max_f32_e32 v54, 0, v54
	v_max_f32_e32 v55, 0, v55
	v_max_f32_e32 v48, 0, v48
	v_max_f32_e32 v49, 0, v49
	v_max_f32_e32 v50, 0, v50
	v_max_f32_e32 v51, 0, v51
	v_pk_mul_f32 v[52:53], v[52:53], v[52:53]
	v_pk_mul_f32 v[54:55], v[54:55], v[54:55]
	v_pk_mul_f32 v[48:49], v[48:49], v[48:49]
	v_pk_mul_f32 v[50:51], v[50:51], v[50:51]
	v_cvt_pk_bf16_f32 v52, v52, v53
	v_cvt_pk_bf16_f32 v53, v54, v55
	v_cvt_pk_bf16_f32 v54, v48, v49
	v_cvt_pk_bf16_f32 v55, v50, v51
	global_store_dwordx4 v178, v[52:55], s[0:1] offset:256 sc1
	s_waitcnt vmcnt(12)
; __device__ __forceinline__ u32x4 pack8(const f32x4 v0, const f32x4 v1) { u32x4 w; w.x = cvt_pk_bf16(v0[0], v0[1]); w.y = cvt_pk_bf16(v0[2], v0[3]); w.z = cvt_pk_bf16(v1[0], v1[1]); w.w = cvt_pk_bf16(v1[2], v1[3]); return w; }
; __device__ __forceinline__ void row_rs8(float (&rs)[8], const float* ssq, int row0, int fq) {
;     ...
;     for (int i = 0; i < 8; ++i) p[i] = *(const f32x4*)(ssq + (size_t)(row0 + (i >> 2) * HALF + (i & 3) * 16) * 16 + 4 * fq);
; #pragma unroll
;     for (int i = 0; i < 8; ++i) { float s = (p[i][0] + p[i][1]) + (p[i][2] + p[i][3]); s += __shfl_xor(s, 16); s += __shfl_xor(s, 32); rs[i] = __builtin_amdgcn_rsqf(s * (1.0f / DMODEL) + RMS_EPS); }
;     __device__ __forceinline__ void operator()(const f32x4 (&acc)[2][2][4][2], const Unit& u, int wr, int wc, int fr, int fq) const {
;     ...
;             for (int m = 0; m < 4; ++m) { const int row = row0 + ai * HALF + m * 16; const float r = rs[ai * 4 + m];
;                 bf16_t* rowp = O + (size_t)row * ldc + col0;
; #pragma unroll
;                 for (int bj = 0; bj < 2; ++bj) { f32x4 v0 = acc[ai][bj][m][0] * r, v1 = acc[ai][bj][m][1] * r;
; #pragma unroll
;                     for (int e = 0; e < 4; ++e) { const float a = fmaxf(v0[e], 0.f), b = fmaxf(v1[e], 0.f); v0[e] = a * a; v1[e] = b * b; }
;                     *(u32x4*)(rowp + bj * HALF) = pack8(v0, v1); } }
	v_add_f32_e32 v176, v148, v149
	v_add_f32_e32 v177, v150, v151
	v_add_f32_e32 v176, v176, v177
	ds_bpermute_b32 v177, v174, v176
	s_waitcnt lgkmcnt(0)
	v_add_f32_e32 v176, v176, v177
	ds_bpermute_b32 v177, v175, v176
	v_add_u32_e32 v178, 0x120000, v172
	s_waitcnt lgkmcnt(0)
	v_add_f32_e32 v176, v176, v177
	v_fmamk_f32 v176, v176, 0x3a800000, v193
	v_rsq_f32_e32 v180, v176
	s_nop 0
	v_pk_mul_f32 v[44:45], v[44:45], v[180:181] op_sel_hi:[1,0]
	v_pk_mul_f32 v[46:47], v[46:47], v[180:181] op_sel_hi:[1,0]
	v_pk_mul_f32 v[40:41], v[40:41], v[180:181] op_sel_hi:[1,0]
	v_pk_mul_f32 v[42:43], v[42:43], v[180:181] op_sel_hi:[1,0]
	v_max_f32_e32 v44, 0, v44
	v_max_f32_e32 v45, 0, v45
	v_max_f32_e32 v46, 0, v46
	v_max_f32_e32 v47, 0, v47
	v_max_f32_e32 v40, 0, v40
	v_max_f32_e32 v41, 0, v41
	v_max_f32_e32 v42, 0, v42
	v_max_f32_e32 v43, 0, v43
	v_pk_mul_f32 v[44:45], v[44:45], v[44:45]
	v_pk_mul_f32 v[46:47], v[46:47], v[46:47]
	v_pk_mul_f32 v[40:41], v[40:41], v[40:41]
	v_pk_mul_f32 v[42:43], v[42:43], v[42:43]
	v_cvt_pk_bf16_f32 v44, v44, v45
	v_cvt_pk_bf16_f32 v45, v46, v47
	v_cvt_pk_bf16_f32 v46, v40, v41
	v_cvt_pk_bf16_f32 v47, v42, v43
	global_store_dwordx4 v178, v[44:47], s[0:1] sc1
	v_pk_mul_f32 v[36:37], v[36:37], v[180:181] op_sel_hi:[1,0]
	v_pk_mul_f32 v[38:39], v[38:39], v[180:181] op_sel_hi:[1,0]
	v_pk_mul_f32 v[32:33], v[32:33], v[180:181] op_sel_hi:[1,0]
	v_pk_mul_f32 v[34:35], v[34:35], v[180:181] op_sel_hi:[1,0]
	v_max_f32_e32 v36, 0, v36
	v_max_f32_e32 v37, 0, v37
	v_max_f32_e32 v38, 0, v38
	v_max_f32_e32 v39, 0, v39
	v_max_f32_e32 v32, 0, v32
	v_max_f32_e32 v33, 0, v33
	v_max_f32_e32 v34, 0, v34
	v_max_f32_e32 v35, 0, v35
	v_pk_mul_f32 v[36:37], v[36:37], v[36:37]
	v_pk_mul_f32 v[38:39], v[38:39], v[38:39]
	v_pk_mul_f32 v[32:33], v[32:33], v[32:33]
	v_pk_mul_f32 v[34:35], v[34:35], v[34:35]
	v_cvt_pk_bf16_f32 v36, v36, v37
	v_cvt_pk_bf16_f32 v37, v38, v39
	v_cvt_pk_bf16_f32 v38, v32, v33
	v_cvt_pk_bf16_f32 v39, v34, v35
	global_store_dwordx4 v178, v[36:39], s[0:1] offset:256 sc1
	s_waitcnt vmcnt(13)
	v_add_f32_e32 v176, v164, v165
	v_add_f32_e32 v177, v166, v167
	v_add_f32_e32 v176, v176, v177
	ds_bpermute_b32 v177, v174, v176
	s_waitcnt lgkmcnt(0)
	v_add_f32_e32 v176, v176, v177
	ds_bpermute_b32 v177, v175, v176
	v_add_u32_e32 v178, 0x140000, v172
	s_waitcnt lgkmcnt(0)
	v_add_f32_e32 v176, v176, v177
	v_fmamk_f32 v176, v176, 0x3a800000, v193
	v_rsq_f32_e32 v180, v176
	s_nop 0
	v_pk_mul_f32 v[28:29], v[28:29], v[180:181] op_sel_hi:[1,0]
	v_pk_mul_f32 v[30:31], v[30:31], v[180:181] op_sel_hi:[1,0]
	v_pk_mul_f32 v[24:25], v[24:25], v[180:181] op_sel_hi:[1,0]
	v_pk_mul_f32 v[26:27], v[26:27], v[180:181] op_sel_hi:[1,0]
	v_max_f32_e32 v28, 0, v28
	v_max_f32_e32 v29, 0, v29
	v_max_f32_e32 v30, 0, v30
	v_max_f32_e32 v31, 0, v31
	v_max_f32_e32 v24, 0, v24
	v_max_f32_e32 v25, 0, v25
	v_max_f32_e32 v26, 0, v26
	v_max_f32_e32 v27, 0, v27
	v_pk_mul_f32 v[28:29], v[28:29], v[28:29]
	v_pk_mul_f32 v[30:31], v[30:31], v[30:31]
	v_pk_mul_f32 v[24:25], v[24:25], v[24:25]
	v_pk_mul_f32 v[26:27], v[26:27], v[26:27]
	v_cvt_pk_bf16_f32 v28, v28, v29
	v_cvt_pk_bf16_f32 v29, v30, v31
	v_cvt_pk_bf16_f32 v30, v24, v25
	v_cvt_pk_bf16_f32 v31, v26, v27
	global_store_dwordx4 v178, v[28:31], s[0:1] sc1
	v_pk_mul_f32 v[20:21], v[20:21], v[180:181] op_sel_hi:[1,0]
	v_pk_mul_f32 v[22:23], v[22:23], v[180:181] op_sel_hi:[1,0]
	v_pk_mul_f32 v[16:17], v[16:17], v[180:181] op_sel_hi:[1,0]
	v_pk_mul_f32 v[18:19], v[18:19], v[180:181] op_sel_hi:[1,0]
	v_max_f32_e32 v20, 0, v20
	v_max_f32_e32 v21, 0, v21
	v_max_f32_e32 v22, 0, v22
	v_max_f32_e32 v23, 0, v23
	v_max_f32_e32 v16, 0, v16
	v_max_f32_e32 v17, 0, v17
	v_max_f32_e32 v18, 0, v18
	v_max_f32_e32 v19, 0, v19
	v_pk_mul_f32 v[20:21], v[20:21], v[20:21]
	v_pk_mul_f32 v[22:23], v[22:23], v[22:23]
	v_pk_mul_f32 v[16:17], v[16:17], v[16:17]
	v_pk_mul_f32 v[18:19], v[18:19], v[18:19]
	v_cvt_pk_bf16_f32 v20, v20, v21
	v_cvt_pk_bf16_f32 v21, v22, v23
	v_cvt_pk_bf16_f32 v22, v16, v17
	v_cvt_pk_bf16_f32 v23, v18, v19
	global_store_dwordx4 v178, v[20:23], s[0:1] offset:256 sc1
	s_waitcnt vmcnt(14)
	v_add_f32_e32 v176, v168, v169
	v_add_f32_e32 v177, v170, v171
	v_add_f32_e32 v176, v176, v177
	ds_bpermute_b32 v177, v174, v176
	s_waitcnt lgkmcnt(0)
	v_add_f32_e32 v176, v176, v177
	ds_bpermute_b32 v177, v175, v176
	v_add_u32_e32 v178, 0x160000, v172
	s_waitcnt lgkmcnt(0)
	v_add_f32_e32 v176, v176, v177
	v_fmamk_f32 v176, v176, 0x3a800000, v193
	v_rsq_f32_e32 v180, v176
	s_nop 0
	v_pk_mul_f32 v[12:13], v[12:13], v[180:181] op_sel_hi:[1,0]
	v_pk_mul_f32 v[14:15], v[14:15], v[180:181] op_sel_hi:[1,0]
	v_pk_mul_f32 v[8:9], v[8:9], v[180:181] op_sel_hi:[1,0]
	v_pk_mul_f32 v[10:11], v[10:11], v[180:181] op_sel_hi:[1,0]
	v_max_f32_e32 v12, 0, v12
	v_max_f32_e32 v13, 0, v13
	v_max_f32_e32 v14, 0, v14
	v_max_f32_e32 v15, 0, v15
	v_max_f32_e32 v8, 0, v8
	v_max_f32_e32 v9, 0, v9
	v_max_f32_e32 v10, 0, v10
	v_max_f32_e32 v11, 0, v11
	v_pk_mul_f32 v[12:13], v[12:13], v[12:13]
	v_pk_mul_f32 v[14:15], v[14:15], v[14:15]
	v_pk_mul_f32 v[8:9], v[8:9], v[8:9]
	v_pk_mul_f32 v[10:11], v[10:11], v[10:11]
	v_cvt_pk_bf16_f32 v12, v12, v13
	v_cvt_pk_bf16_f32 v13, v14, v15
	v_cvt_pk_bf16_f32 v14, v8, v9
	v_cvt_pk_bf16_f32 v15, v10, v11
	global_store_dwordx4 v178, v[12:15], s[0:1] sc1
	v_pk_mul_f32 v[4:5], v[4:5], v[180:181] op_sel_hi:[1,0]
	v_pk_mul_f32 v[6:7], v[6:7], v[180:181] op_sel_hi:[1,0]
	v_pk_mul_f32 v[0:1], v[0:1], v[180:181] op_sel_hi:[1,0]
	v_pk_mul_f32 v[2:3], v[2:3], v[180:181] op_sel_hi:[1,0]
	v_max_f32_e32 v4, 0, v4
	v_max_f32_e32 v5, 0, v5
	v_max_f32_e32 v6, 0, v6
	v_max_f32_e32 v7, 0, v7
	v_max_f32_e32 v0, 0, v0
	v_max_f32_e32 v1, 0, v1
	v_max_f32_e32 v2, 0, v2
	v_max_f32_e32 v3, 0, v3
	v_pk_mul_f32 v[4:5], v[4:5], v[4:5]
	v_pk_mul_f32 v[6:7], v[6:7], v[6:7]
	v_pk_mul_f32 v[0:1], v[0:1], v[0:1]
	v_pk_mul_f32 v[2:3], v[2:3], v[2:3]
	v_cvt_pk_bf16_f32 v4, v4, v5
	v_cvt_pk_bf16_f32 v5, v6, v7
	v_cvt_pk_bf16_f32 v6, v0, v1
	v_cvt_pk_bf16_f32 v7, v2, v3
	global_store_dwordx4 v178, v[4:7], s[0:1] offset:256 sc1
	s_mov_b64 s[26:27], -1
	s_andn2_b64 vcc, exec, s[14:15]
	s_mov_b64 s[14:15], -1
	s_cbranch_vccnz .LBB0_601
	s_andn2_b64 vcc, exec, s[4:5]
	s_cbranch_vccnz .LBB0_600
	s_barrier
	s_branch .LBB0_600
